# MLA interior loop: static s_setprio 1 for waves 4-7
# speedup vs baseline: 1.0070x; 1.0070x over previous
; __device__ __forceinline__ int otid() { int t = threadIdx.x; asm volatile("" : "+v"(t)); return t; }
; __device__ __forceinline__ void attn_unit_sm(int b, int h, int qb, const bf16_t* __restrict__ Q, const bf16_t* __restrict__ K, const bf16_t* __restrict__ K2, const bf16_t* __restrict__ Vt, bf16_t* __restrict__ O, const float* __restrict__ cs, LAS unsigned char* lds, int var) {
;     ...
;     const int tid = otid(), lane = tid & 63, wid = __builtin_amdgcn_readfirstlane(tid >> 6), q32 = lane & 31, hi = lane >> 5;
;     const long rowbase = (long)b * SEQ; const int q0 = qb * 256;
;     LAS float* wsf = (LAS float*)(lds + OFF_WS) + wid * 64;
;     bf16x8 qr[ND];
;     { const bf16_t* qp = Q + (rowbase + q0 + wid * 32 + q32) * ldq + h * 96 + hi * 8;
; #pragma unroll
;       for (int d0 = 0; d0 < ND; ++d0) qr[d0] = *(const bf16x8*)(qp + d0 * 16); }
;     const int qpos = q0 + wid * 32 + q32, ns = (q0 + 256) / 128, jmax = (q0 + wid * 32 + 31) / 64;
;     const int krow = tid >> 3, kch = tid & 7;
;     const bf16_t* kg = K + (rowbase + krow) * ldk + h * 64 + kch * 8;
;     const bf16_t* vg = Vt + (long)(h * 64 + krow) * T_TOK + rowbase + kch * 8;
;     const bf16_t* k2g = K2 + (rowbase + (tid >> 2)) * 32 + (tid & 3) * 8;
;     const int kw = krow * KP + kch * 16, vw = krow * VP + kch * 16, k2w = (tid >> 2) * KP + 128 + (tid & 3) * 16;
;     u32x4 kreg0, kreg1, vreg0, vreg1, k2reg;
;     ...
;     SM_LOAD(0);
;     {
;         const float* cr = cs + (rowbase + q0 + wid * 32 + q32) * 32 + 8 * hi;
;         const f32x4 c0 = *(const f32x4*)cr, c1 = *(const f32x4*)(cr + 4), s0 = *(const f32x4*)(cr + 16), s1 = *(const f32x4*)(cr + 20);
;         const float cc[8] = {c0[0], c0[1], c0[2], c0[3], c1[0], c1[1], c1[2], c1[3]}, ss[8] = {s0[0], s0[1], s0[2], s0[3], s1[0], s1[1], s1[2], s1[3]};
;         float ra[8], rb[8];
; #pragma unroll
;         for (int i = 0; i < 8; ++i) { const float t1 = bf2f((unsigned short)qr[4][i]), t2 = bf2f((unsigned short)qr[5][i]); ra[i] = t1 * cc[i] - t2 * ss[i]; rb[i] = t1 * ss[i] + t2 * cc[i]; }
;         u32x4 wa, wb; wa.x = pk2(ra[0], ra[1]); wa.y = pk2(ra[2], ra[3]); wa.z = pk2(ra[4], ra[5]); wa.w = pk2(ra[6], ra[7]); wb.x = pk2(rb[0], rb[1]); wb.y = pk2(rb[2], rb[3]); wb.z = pk2(rb[4], rb[5]); wb.w = pk2(rb[6], rb[7]);
;         qr[4] = __builtin_bit_cast(bf16x8, wa); qr[5] = __builtin_bit_cast(bf16x8, wb); }
;     SM_STORE(0); __syncthreads();
.LBB0_44:
	s_ashr_i32 s10, s5, 4
	v_mov_b32_e32 v1, v228
	s_and_b32 s4, s5, 15
	s_ashr_i32 s11, s10, 31
	v_readfirstlane_b32 s6, v1
	s_lshl_b32 s5, s0, 8
	s_lshl_b64 s[18:19], s[10:11], 13
	s_and_b32 s20, s6, 0x3fffffc0
	s_ashr_i32 s0, s5, 31
	s_add_u32 s7, s18, s5
	s_addc_u32 s0, s19, s0
	s_ashr_i32 s42, s6, 1
	s_andn2_b32 s42, s42, 31
	s_ashr_i32 s12, s42, 31
	s_add_u32 s6, s7, s42
	s_addc_u32 s7, s0, s12
	v_readlane_b32 s12, v254, 32
	v_and_b32_e32 v169, 31, v1
	v_readlane_b32 s13, v254, 33
	v_or_b32_e32 v2, s6, v169
	s_movk_i32 s0, 0xc00
	v_mov_b64_e32 v[4:5], s[12:13]
	v_mad_u64_u32 v[4:5], s[12:13], v2, s0, v[4:5]
	v_mov_b32_e32 v3, 0xc00
	v_bfe_u32 v168, v1, 5, 1
	v_mad_i32_i24 v5, s7, v3, v5
	s_mul_i32 s0, s4, 0xc0
	v_mov_b32_e32 v3, s7
	v_readlane_b32 s12, v254, 40
	v_lshl_add_u64 v[4:5], v[4:5], 0, s[0:1]
	v_lshlrev_b32_e32 v148, 4, v168
	v_mov_b32_e32 v149, v0
	v_lshlrev_b64 v[2:3], 7, v[2:3]
	v_readlane_b32 s13, v254, 41
	s_waitcnt vmcnt(4)
	v_lshl_add_u64 v[38:39], v[4:5], 0, v[148:149]
	v_lshlrev_b32_e32 v4, 5, v168
	v_lshl_add_u64 v[2:3], s[12:13], 0, v[2:3]
	v_mov_b32_e32 v5, v0
	v_ashrrev_i32_e32 v40, 3, v1
	v_lshl_add_u64 v[2:3], v[2:3], 0, v[4:5]
	v_ashrrev_i32_e32 v41, 31, v40
	global_load_dwordx4 v[14:17], v[38:39], off offset:128
	global_load_dwordx4 v[18:21], v[38:39], off offset:160
	global_load_dwordx4 v[22:25], v[2:3], off offset:64
	global_load_dwordx4 v[26:29], v[2:3], off
	global_load_dwordx4 v[30:33], v[2:3], off offset:16
	global_load_dwordx4 v[34:37], v[2:3], off offset:80
	v_lshl_add_u64 v[2:3], s[18:19], 0, v[40:41]
	v_readlane_b32 s12, v254, 34
	v_lshlrev_b64 v[2:3], 11, v[2:3]
	v_readlane_b32 s13, v254, 35
	s_lshl_b32 s0, s4, 7
	v_lshlrev_b32_e32 v44, 4, v1
	v_lshl_add_u64 v[2:3], s[12:13], 0, v[2:3]
	v_lshl_add_u64 v[2:3], v[2:3], 0, s[0:1]
	v_and_b32_e32 v154, 0x70, v44
	v_mov_b32_e32 v155, v0
	s_lshl_b32 s24, s4, 6
	v_lshl_add_u64 v[6:7], v[2:3], 0, v[154:155]
	s_mov_b32 s12, 0x20000
	v_add_u32_e32 v8, s24, v40
	v_add_co_u32_e32 v2, vcc, s12, v6
	v_ashrrev_i32_e32 v9, 31, v8
	v_readlane_b32 s12, v254, 36
	v_ashrrev_i32_e32 v42, 2, v1
	v_lshlrev_b64 v[8:9], 15, v[8:9]
	v_readlane_b32 s13, v254, 37
	v_ashrrev_i32_e32 v43, 31, v42
	v_addc_co_u32_e32 v3, vcc, 0, v7, vcc
	v_lshl_add_u64 v[10:11], s[12:13], 0, v[8:9]
	v_lshl_add_u64 v[8:9], s[18:19], 0, v[42:43]
	v_lshlrev_b64 v[12:13], 6, v[8:9]
	v_lshl_add_u64 v[12:13], s[8:9], 0, v[12:13]
	v_and_b32_e32 v44, 48, v44
	v_mov_b32_e32 v45, v0
	global_load_dwordx4 v[2:5], v[2:3], off
	v_lshl_add_u64 v[12:13], v[12:13], 0, v[44:45]
	global_load_dwordx4 v[6:9], v[6:7], off
	s_lshl_b64 s[12:13], s[10:11], 14
	global_load_dwordx4 v[112:115], v[12:13], off
	v_lshl_add_u64 v[10:11], v[10:11], 0, s[12:13]
	v_lshl_add_u64 v[46:47], v[10:11], 0, v[154:155]
	global_load_dwordx4 v[10:13], v[46:47], off
	global_load_dwordx4 v[108:111], v[46:47], off offset:128
	global_load_dwordx4 v[84:87], v[38:39], off
	global_load_dwordx4 v[88:91], v[38:39], off offset:32
	global_load_dwordx4 v[92:95], v[38:39], off offset:64
	global_load_dwordx4 v[96:99], v[38:39], off offset:96
	s_movk_i32 s19, 0x108
	v_mul_lo_u32 v45, v40, s19
	s_add_i32 s19, s5, 0x100
	v_lshlrev_b32_e32 v155, 3, v168
	s_lshl_b32 s20, s20, 2
	s_ashr_i32 s37, s19, 7
	s_movk_i32 s19, 0xd0
	s_add_i32 s25, s20, 0
	v_mad_u64_u32 v[150:151], s[20:21], v40, s19, v[154:155]
	v_mad_u64_u32 v[152:153], s[20:21], v42, s19, v[44:45]
	v_add3_u32 v151, 0, v45, v154
	s_add_i32 s25, s25, 0x15400
	s_mov_b32 s18, 0
	s_mov_b32 s19, 0
	s_cmp_lt_i32 s37, 3
	v_lshlrev_b64 v[158:159], 15, v[40:41]
	v_lshlrev_b64 v[160:161], 6, v[42:43]
	v_and_b32_e32 v172, 3, v1
	v_lshlrev_b64 v[156:157], 11, v[40:41]
	v_mul_u32_u24_e32 v173, 0x108, v169
	v_cmp_eq_u32_e64 s[40:41], 0, v168
	v_lshl_add_u32 v149, v169, 2, s25
	v_mul_u32_u24_e32 v153, 0xd0, v169
	s_waitcnt vmcnt(14)
	v_and_b32_e32 v39, 0xffff0000, v14
	v_lshlrev_b32_e32 v38, 16, v14
	s_waitcnt vmcnt(13)
	v_and_b32_e32 v47, 0xffff0000, v18
	v_lshlrev_b32_e32 v46, 16, v18
	v_and_b32_e32 v49, 0xffff0000, v15
	v_lshlrev_b32_e32 v48, 16, v15
	v_and_b32_e32 v15, 0xffff0000, v19
	v_lshlrev_b32_e32 v14, 16, v19
	s_waitcnt vmcnt(12)
	v_pk_mul_f32 v[18:19], v[22:23], v[46:47]
	v_pk_mul_f32 v[22:23], v[22:23], v[38:39]
	s_waitcnt vmcnt(11)
	v_pk_fma_f32 v[18:19], v[26:27], v[38:39], v[18:19] neg_lo:[0,0,1] neg_hi:[0,0,1]
	v_pk_fma_f32 v[22:23], v[26:27], v[46:47], v[22:23]
	v_pk_mul_f32 v[26:27], v[24:25], v[14:15]
	v_pk_mul_f32 v[24:25], v[24:25], v[48:49]
	v_pk_fma_f32 v[26:27], v[28:29], v[48:49], v[26:27] neg_lo:[0,0,1] neg_hi:[0,0,1]
	v_pk_fma_f32 v[14:15], v[28:29], v[14:15], v[24:25]
	v_and_b32_e32 v29, 0xffff0000, v20
	v_lshlrev_b32_e32 v28, 16, v20
	v_and_b32_e32 v25, 0xffff0000, v16
	v_lshlrev_b32_e32 v24, 16, v16
	s_waitcnt vmcnt(9)
	v_pk_mul_f32 v[38:39], v[34:35], v[28:29]
	v_lshlrev_b32_e32 v16, 16, v21
	v_pk_fma_f32 v[38:39], v[30:31], v[24:25], v[38:39] neg_lo:[0,0,1] neg_hi:[0,0,1]
	v_pk_mul_f32 v[24:25], v[34:35], v[24:25]
	v_cvt_pk_bf16_f32 v105, v14, v15
	v_pk_fma_f32 v[24:25], v[30:31], v[28:29], v[24:25]
	v_and_b32_e32 v29, 0xffff0000, v17
	v_lshlrev_b32_e32 v28, 16, v17
	v_and_b32_e32 v17, 0xffff0000, v21
	v_pk_mul_f32 v[20:21], v[36:37], v[16:17]
	v_add_u32_e32 v14, 0, v150
	v_pk_fma_f32 v[20:21], v[32:33], v[28:29], v[20:21] neg_lo:[0,0,1] neg_hi:[0,0,1]
	v_pk_mul_f32 v[28:29], v[36:37], v[28:29]
	s_waitcnt vmcnt(7)
	ds_write_b128 v14, v[6:9]
	ds_write_b128 v14, v[2:5] offset:13312
	v_add_u32_e32 v14, 0, v152
	v_pk_fma_f32 v[16:17], v[32:33], v[16:17], v[28:29]
	s_waitcnt vmcnt(6)
	ds_write_b128 v14, v[112:115] offset:128
	v_add_u32_e32 v14, 0xd000, v151
	v_cvt_pk_bf16_f32 v100, v18, v19
	v_cvt_pk_bf16_f32 v101, v26, v27
	v_cvt_pk_bf16_f32 v102, v38, v39
	v_cvt_pk_bf16_f32 v103, v20, v21
	v_cvt_pk_bf16_f32 v104, v22, v23
	v_cvt_pk_bf16_f32 v106, v24, v25
	v_cvt_pk_bf16_f32 v107, v16, v17
	s_waitcnt vmcnt(5)
	ds_write2_b64 v14, v[10:11], v[12:13] offset1:1
	v_add_u32_e32 v14, 0xd080, v151
	s_waitcnt vmcnt(4)
	ds_write2_b64 v14, v[108:109], v[110:111] offset1:1
	s_waitcnt lgkmcnt(0)
	s_barrier
; __device__ __forceinline__ void attn_unit_sm(int b, int h, int qb, const bf16_t* __restrict__ Q, const bf16_t* __restrict__ K, const bf16_t* __restrict__ K2, const bf16_t* __restrict__ Vt, bf16_t* __restrict__ O, const float* __restrict__ cs, LAS unsigned char* lds, int var) {
;     ...
;     SmState st;
; #pragma unroll
;     for (int r = 0; r < 16; ++r) { st.o0[r] = 0.f; st.o1[r] = 0.f; }
;     st.mrun = -INFINITY; st.lrun = 0.f;
;     int it = 0;
;     for (; it < ns - 2; ++it) {
	s_cbranch_scc1 .LBB0_57
	s_add_i32 s18, s37, -2
	s_lshl_b32 s20, s4, 21
	s_add_u32 s20, s12, s20
	s_addc_u32 s21, s13, 0
	v_lshl_add_u64 v[162:163], s[20:21], 0, v[158:159]
	s_lshl_b64 s[20:21], s[10:11], 19
	s_add_u32 s20, s20, 0x14462000
	s_addc_u32 s21, s21, 0
	v_lshl_add_u64 v[164:165], s[20:21], 0, v[160:161]
	s_lshl_b64 s[20:21], s[10:11], 24
	v_mov_b32_e32 v14, v0
	v_mov_b32_e32 v15, v0
	v_lshl_add_u64 v[166:167], s[20:21], 0, v[156:157]
	v_mov_b32_e32 v1, v0
	v_mov_b32_e32 v2, v0
	v_mov_b32_e32 v3, v0
	v_mov_b32_e32 v4, v0
	v_mov_b32_e32 v5, v0
	v_mov_b32_e32 v6, v0
	v_mov_b32_e32 v7, v0
	v_mov_b32_e32 v8, v0
	v_mov_b32_e32 v9, v0
	v_mov_b32_e32 v10, v0
	v_mov_b32_e32 v11, v0
	v_mov_b32_e32 v12, v0
	v_mov_b32_e32 v13, v0
	v_mov_b64_e32 v[30:31], v[14:15]
	v_mov_b64_e32 v[46:47], v[14:15]
	v_add3_u32 v174, 0, v173, v155
	v_add3_u32 v175, 0, v148, v153
	v_or_b32_e32 v162, v162, v154
	v_lshl_or_b32 v164, v172, 4, v164
	v_or3_b32 v166, v166, s0, v154
	v_mov_b32_e32 v170, 0
	v_mov_b32_e32 v171, 0xff800000
	v_mov_b32_e32 v197, 0xff800000
	v_mov_b32_e32 v198, 0
	v_mov_b32_e32 v199, 0
	v_mov_b32_e32 v200, 0
	v_mov_b32_e32 v201, 0
	v_mov_b32_e32 v202, 0
	v_mov_b32_e32 v203, 0
	v_mov_b32_e32 v204, 0
	v_mov_b32_e32 v205, 0
	v_mov_b32_e32 v206, 0
	v_mov_b32_e32 v207, 0
	v_mov_b32_e32 v208, 0
	v_mov_b32_e32 v209, 0
	v_mov_b32_e32 v210, 0
	v_mov_b32_e32 v211, 0
	v_mov_b32_e32 v212, 0
	v_mov_b32_e32 v213, 0
	v_mov_b64_e32 v[28:29], v[12:13]
	v_mov_b64_e32 v[26:27], v[10:11]
	v_mov_b64_e32 v[24:25], v[8:9]
	v_mov_b64_e32 v[22:23], v[6:7]
	v_mov_b64_e32 v[20:21], v[4:5]
	v_mov_b64_e32 v[18:19], v[2:3]
	v_mov_b64_e32 v[16:17], v[0:1]
	v_mov_b64_e32 v[44:45], v[12:13]
	v_mov_b64_e32 v[42:43], v[10:11]
	v_mov_b64_e32 v[40:41], v[8:9]
	v_mov_b64_e32 v[38:39], v[6:7]
	v_mov_b64_e32 v[36:37], v[4:5]
	v_mov_b64_e32 v[34:35], v[2:3]
	v_mov_b64_e32 v[32:33], v[0:1]
	v_readfirstlane_b32 s98, v228
	s_cmp_lt_u32 s98, 0x100
	s_cbranch_scc1 .LBB0_48
	s_setprio 1
	s_branch .LBB0_48

; __device__ __forceinline__ unsigned pk2(float lo, float hi) { f32x2_t v = {lo, hi}; bf16x2_t b = __builtin_convertvector(v, bf16x2_t); return __builtin_bit_cast(unsigned, b); }
; __device__ __forceinline__ float ex2(float x) { return __builtin_amdgcn_exp2f(x); }
; #define MFMA32(a, b, c) __builtin_amdgcn_mfma_f32_32x32x16_bf16((a), (b), (c), 0, 0, 0)
; template <bool MASK> __device__ __forceinline__ void sm_tile(f32x16& p0, f32x16& p1, float& mrun, float& lrun, f32x16& o0, f32x16& o1, LAS float* wsf, int kv0, int qpos, int q32, int hi) {
;     ...
;     for (int r = 0; r < 16; ++r) { p0[r] = ex2(p0[r] - mrun); p1[r] = ex2(p1[r] - mrun); rs += p0[r] + p1[r]; }
;     rs += xhalf(rs, hi); lrun += rs;
; template <bool MASK> __device__ __forceinline__ void sm_iter(int var, SmState& st, const bf16x8 (&qr)[6], const LAS unsigned char* kb, const LAS unsigned char* vb, LAS float* wsf, int kv0, int qpos, int q32, int hi) {
;     ...
;     for (int j = 0; j < 4; ++j) {
;         u32x4 pw;
;         if (j < 2) { const int r0 = 8 * (j & 1); pw.x = pk2(p0[r0], p0[r0 + 1]); pw.y = pk2(p0[r0 + 2], p0[r0 + 3]); pw.z = pk2(p0[r0 + 4], p0[r0 + 5]); pw.w = pk2(p0[r0 + 6], p0[r0 + 7]); }
;         else { const int r0 = 8 * (j & 1); pw.x = pk2(p1[r0], p1[r0 + 1]); pw.y = pk2(p1[r0 + 2], p1[r0 + 3]); pw.z = pk2(p1[r0 + 4], p1[r0 + 5]); pw.w = pk2(p1[r0 + 6], p1[r0 + 7]); }
;         const bf16x8 pa = __builtin_bit_cast(bf16x8, pw);
;         { const s16x4 lo = vlo[2 * j], hh = vhh[2 * j]; const bf16x8 vf = {lo[0], lo[1], lo[2], lo[3], hh[0], hh[1], hh[2], hh[3]}; st.o0 = MFMA32(pa, vf, st.o0); }
;         { const s16x4 lo = vlo[2 * j + 1], hh = vhh[2 * j + 1]; const bf16x8 vf = {lo[0], lo[1], lo[2], lo[3], hh[0], hh[1], hh[2], hh[3]}; st.o1 = MFMA32(pa, vf, st.o1); }
;     }
.Lm3_drain:
	v_exp_f32_e32 v48, v48
	v_exp_f32_e32 v49, v49
	v_exp_f32_e32 v50, v50
	v_add_f32_e32 v15, v48, v49
	v_exp_f32_e32 v51, v51
	v_cvt_pk_bf16_f32 v214, v48, v49
	v_exp_f32_e32 v52, v52
	v_add_f32_e32 v177, v50, v51
	v_exp_f32_e32 v53, v53
	v_cvt_pk_bf16_f32 v215, v50, v51
	v_exp_f32_e32 v54, v54
	v_add_f32_e32 v15, v15, v52
	v_exp_f32_e32 v55, v55
	v_add_f32_e32 v177, v177, v53
	v_exp_f32_e32 v56, v56
	v_cvt_pk_bf16_f32 v216, v52, v53
	v_exp_f32_e32 v57, v57
	v_add_f32_e32 v15, v15, v54
	v_exp_f32_e32 v58, v58
	v_add_f32_e32 v177, v177, v55
	v_exp_f32_e32 v59, v59
	v_cvt_pk_bf16_f32 v217, v54, v55
	v_exp_f32_e32 v60, v60
	v_add_f32_e32 v15, v15, v56
	v_exp_f32_e32 v61, v61
	v_add_f32_e32 v177, v177, v57
	v_exp_f32_e32 v62, v62
	v_cvt_pk_bf16_f32 v218, v56, v57
	v_exp_f32_e32 v63, v63
	v_add_f32_e32 v15, v15, v58
	v_add_f32_e32 v177, v177, v59
	v_cvt_pk_bf16_f32 v219, v58, v59
	v_add_f32_e32 v15, v15, v60
	v_add_f32_e32 v177, v177, v61
	v_cvt_pk_bf16_f32 v220, v60, v61
	v_add_f32_e32 v15, v15, v62
	v_add_f32_e32 v177, v177, v63
	v_cvt_pk_bf16_f32 v221, v62, v63
	v_add_f32_e32 v15, v15, v177
	v_add_f32_e32 v170, v170, v15
	s_nop 1
	v_mfma_f32_32x32x16_bf16 v[16:31], v[214:217], v[140:143], v[16:31]
	v_mfma_f32_32x32x16_bf16 v[32:47], v[214:217], v[144:147], v[32:47]
	v_mfma_f32_32x32x16_bf16 v[16:31], v[218:221], v[180:183], v[16:31]
	v_mfma_f32_32x32x16_bf16 v[32:47], v[218:221], v[184:187], v[32:47]
	v_mov_b32_e32 v15, v170
	v_mov_b32_e32 v177, v170
	v_sub_f32_e32 v171, 0, v198
	s_nop 0
	v_permlane32_swap_b32_e32 v15, v177
	v_add_f32_e32 v170, v15, v177
	s_setprio 0
	s_branch .LBB0_58

; __global__ void __launch_bounds__(512, 2) mk_fwd(Args args) {
	.amdhsa_kernel _Z6mk_fwd4Args
		.amdhsa_group_segment_fixed_size 0
		.amdhsa_private_segment_fixed_size 0
		.amdhsa_kernarg_size 472
		.amdhsa_user_sgpr_count 2
		.amdhsa_user_sgpr_dispatch_ptr 0
		.amdhsa_user_sgpr_queue_ptr 0
		.amdhsa_user_sgpr_kernarg_segment_ptr 1
		.amdhsa_user_sgpr_dispatch_id 0
		.amdhsa_user_sgpr_kernarg_preload_length 0
		.amdhsa_user_sgpr_kernarg_preload_offset 0
		.amdhsa_user_sgpr_private_segment_size 0
		.amdhsa_uses_dynamic_stack 0
		.amdhsa_enable_private_segment 0
		.amdhsa_system_sgpr_workgroup_id_x 1
		.amdhsa_system_sgpr_workgroup_id_y 0
		.amdhsa_system_sgpr_workgroup_id_z 0
		.amdhsa_system_sgpr_workgroup_info 0
		.amdhsa_system_vgpr_workitem_id 2
		.amdhsa_next_free_vgpr 256
		.amdhsa_next_free_sgpr 102
		.amdhsa_accum_offset 256
		.amdhsa_reserve_vcc 1
		.amdhsa_float_round_mode_32 0
		.amdhsa_float_round_mode_16_64 0
		.amdhsa_float_denorm_mode_32 3
		.amdhsa_float_denorm_mode_16_64 3
		.amdhsa_dx10_clamp 1
		.amdhsa_ieee_mode 1
		.amdhsa_fp16_overflow 0
		.amdhsa_tg_split 0
		.amdhsa_exception_fp_ieee_invalid_op 0
		.amdhsa_exception_fp_denorm_src 0
		.amdhsa_exception_fp_ieee_div_zero 0
		.amdhsa_exception_fp_ieee_overflow 0
		.amdhsa_exception_fp_ieee_underflow 0
		.amdhsa_exception_fp_ieee_inexact 0
		.amdhsa_exception_int_div_zero 0
	.end_amdhsa_kernel

; __global__ void __launch_bounds__(512, 2) mk_fwd(Args args) {
amdhsa.kernels:
  - .agpr_count:     0
    .args:
      - .offset:         0
        .size:           216
        .value_kind:     by_value
      - .offset:         216
        .size:           4
        .value_kind:     hidden_block_count_x
      - .offset:         220
        .size:           4
        .value_kind:     hidden_block_count_y
      - .offset:         224
        .size:           4
        .value_kind:     hidden_block_count_z
      - .offset:         228
        .size:           2
        .value_kind:     hidden_group_size_x
      - .offset:         230
        .size:           2
        .value_kind:     hidden_group_size_y
      - .offset:         232
        .size:           2
        .value_kind:     hidden_group_size_z
      - .offset:         234
        .size:           2
        .value_kind:     hidden_remainder_x
      - .offset:         236
        .size:           2
        .value_kind:     hidden_remainder_y
      - .offset:         238
        .size:           2
        .value_kind:     hidden_remainder_z
      - .offset:         256
        .size:           8
        .value_kind:     hidden_global_offset_x
      - .offset:         264
        .size:           8
        .value_kind:     hidden_global_offset_y
      - .offset:         272
        .size:           8
        .value_kind:     hidden_global_offset_z
      - .offset:         280
        .size:           2
        .value_kind:     hidden_grid_dims
      - .offset:         304
        .size:           8
        .value_kind:     hidden_multigrid_sync_arg
      - .offset:         336
        .size:           4
        .value_kind:     hidden_dynamic_lds_size
    .group_segment_fixed_size: 0
    .kernarg_segment_align: 8
    .kernarg_segment_size: 472
    .language:       OpenCL C
    .language_version:
      - 2
      - 0
    .max_flat_workgroup_size: 512
    .name:           _Z6mk_fwd4Args
    .private_segment_fixed_size: 0
    .sgpr_count:     108
    .sgpr_spill_count: 198
    .symbol:         _Z6mk_fwd4Args.kd
    .uniform_work_group_size: 1
    .uses_dynamic_stack: false
    .vgpr_count:     256
    .vgpr_spill_count: 0
    .wavefront_size: 64
